# P1+P7 epilogue: second-half bias loads hoisted next to first-half loads, counted vmcnt(2)/vmcnt(8) instead of vmcnt(0)
# baseline (speedup 1.0000x reference)
.LBB0_197:
	v_add_u32_e32 v158, s41, v149
	v_ashrrev_i32_e32 v159, 31, v158
	v_lshlrev_b64 v[158:159], 11, v[158:159]
	v_lshl_add_u64 v[158:159], s[60:61], 0, v[158:159]
	v_lshl_add_u64 v[158:159], v[158:159], 0, s[20:21]
	v_ashrrev_i32_e32 v149, 31, v148
	v_lshl_add_u64 v[148:149], v[148:149], 1, v[158:159]
	s_and_b64 vcc, exec, s[10:11]
	s_cbranch_vccnz .Lhb_null1
	v_lshl_add_u64 v[170:171], v[150:151], 2, s[58:59]
	global_load_dwordx4 v[162:165], v[170:171], off offset:512
	global_load_dwordx4 v[166:169], v[170:171], off offset:528
	s_branch .Lhb_done1
.Lhb_null1:
	v_mov_b32_e32 v162, 0
	v_mov_b32_e32 v163, 0
	v_mov_b32_e32 v164, 0
	v_mov_b32_e32 v165, 0
	v_mov_b32_e32 v166, 0
	v_mov_b32_e32 v167, 0
	v_mov_b32_e32 v168, 0
	v_mov_b32_e32 v169, 0
.Lhb_done1:
	s_waitcnt vmcnt(2)
	v_pk_add_f32 v[128:129], v[128:129], v[136:137]
	v_pk_add_f32 v[126:127], v[126:127], v[134:135]
	v_pk_add_f32 v[158:159], v[124:125], v[132:133]
	v_pk_add_f32 v[124:125], v[122:123], v[130:131]
	v_cvt_pk_bf16_f32 v122, v126, v127
	v_cvt_pk_bf16_f32 v123, v128, v129
	v_pk_add_f32 v[118:119], v[118:119], v[134:135]
	v_pk_add_f32 v[114:115], v[114:115], v[130:131]
	v_cvt_pk_bf16_f32 v124, v124, v125
	v_cvt_pk_bf16_f32 v125, v158, v159
	global_store_dwordx4 v[148:149], v[122:125], off
	v_pk_add_f32 v[120:121], v[120:121], v[136:137]
	v_pk_add_f32 v[110:111], v[110:111], v[134:135]
	v_pk_add_f32 v[122:123], v[116:117], v[132:133]
	v_cvt_pk_bf16_f32 v116, v118, v119
	v_cvt_pk_bf16_f32 v117, v120, v121
	v_cvt_pk_bf16_f32 v118, v114, v115
	v_add_co_u32_e32 v114, vcc, s72, v148
	v_pk_add_f32 v[106:107], v[106:107], v[130:131]
	s_nop 0
	v_addc_co_u32_e32 v115, vcc, 0, v149, vcc
	v_cvt_pk_bf16_f32 v119, v122, v123
	global_store_dwordx4 v[114:115], v[116:119], off
	v_pk_add_f32 v[112:113], v[112:113], v[136:137]
	v_pk_add_f32 v[102:103], v[102:103], v[134:135]
	v_pk_add_f32 v[116:117], v[108:109], v[132:133]
	v_cvt_pk_bf16_f32 v108, v110, v111
	v_cvt_pk_bf16_f32 v109, v112, v113
	v_cvt_pk_bf16_f32 v110, v106, v107
	v_add_co_u32_e32 v106, vcc, s27, v148
	v_pk_add_f32 v[98:99], v[98:99], v[130:131]
	s_nop 0
	v_addc_co_u32_e32 v107, vcc, 0, v149, vcc
	v_cvt_pk_bf16_f32 v111, v116, v117
	global_store_dwordx4 v[106:107], v[108:111], off
	v_pk_add_f32 v[104:105], v[104:105], v[136:137]
	v_pk_add_f32 v[94:95], v[94:95], v[134:135]
	v_pk_add_f32 v[108:109], v[100:101], v[132:133]
	v_cvt_pk_bf16_f32 v100, v102, v103
	v_cvt_pk_bf16_f32 v101, v104, v105
	v_cvt_pk_bf16_f32 v102, v98, v99
	v_add_co_u32_e32 v98, vcc, s71, v148
	v_pk_add_f32 v[90:91], v[90:91], v[130:131]
	s_nop 0
	v_addc_co_u32_e32 v99, vcc, 0, v149, vcc
	v_cvt_pk_bf16_f32 v103, v108, v109
	global_store_dwordx4 v[98:99], v[100:103], off
	v_pk_add_f32 v[96:97], v[96:97], v[136:137]
	v_pk_add_f32 v[86:87], v[86:87], v[134:135]
	v_pk_add_f32 v[100:101], v[92:93], v[132:133]
	v_cvt_pk_bf16_f32 v92, v94, v95
	v_cvt_pk_bf16_f32 v93, v96, v97
	v_cvt_pk_bf16_f32 v94, v90, v91
	v_add_co_u32_e32 v90, vcc, s77, v148
	v_pk_add_f32 v[82:83], v[82:83], v[130:131]
	s_nop 0
	v_addc_co_u32_e32 v91, vcc, 0, v149, vcc
	v_cvt_pk_bf16_f32 v95, v100, v101
	global_store_dwordx4 v[90:91], v[92:95], off
	v_pk_add_f32 v[88:89], v[88:89], v[136:137]
	v_pk_add_f32 v[78:79], v[78:79], v[134:135]
	v_pk_add_f32 v[92:93], v[84:85], v[132:133]
	v_cvt_pk_bf16_f32 v84, v86, v87
	v_cvt_pk_bf16_f32 v85, v88, v89
	v_cvt_pk_bf16_f32 v86, v82, v83
	v_add_co_u32_e32 v82, vcc, s78, v148
	v_pk_add_f32 v[74:75], v[74:75], v[130:131]
	s_nop 0
	v_addc_co_u32_e32 v83, vcc, 0, v149, vcc
	v_cvt_pk_bf16_f32 v87, v92, v93
	global_store_dwordx4 v[82:83], v[84:87], off
	v_pk_add_f32 v[80:81], v[80:81], v[136:137]
	v_pk_add_f32 v[70:71], v[70:71], v[134:135]
	v_pk_add_f32 v[84:85], v[76:77], v[132:133]
	v_cvt_pk_bf16_f32 v76, v78, v79
	v_cvt_pk_bf16_f32 v77, v80, v81
	v_cvt_pk_bf16_f32 v78, v74, v75
	v_add_co_u32_e32 v74, vcc, s79, v148
	v_cvt_pk_bf16_f32 v79, v84, v85
	v_pk_add_f32 v[72:73], v[72:73], v[136:137]
	s_nop 0
	v_addc_co_u32_e32 v75, vcc, 0, v149, vcc
	global_store_dwordx4 v[74:75], v[76:79], off
	s_nop 1
	v_pk_add_f32 v[76:77], v[68:69], v[132:133]
	v_pk_add_f32 v[68:69], v[66:67], v[130:131]
	v_cvt_pk_bf16_f32 v66, v70, v71
	v_add_co_u32_e32 v70, vcc, 0x58000, v148
	v_cvt_pk_bf16_f32 v67, v72, v73
	v_cvt_pk_bf16_f32 v68, v68, v69
	v_cvt_pk_bf16_f32 v69, v76, v77
	v_mov_b32_e32 v72, 0
	s_nop 0
	v_addc_co_u32_e32 v71, vcc, 0, v149, vcc
	global_store_dwordx4 v[70:71], v[66:69], off
	s_waitcnt vmcnt(8)
	v_pk_add_f32 v[64:65], v[64:65], v[164:165]
	v_pk_add_f32 v[62:63], v[62:63], v[162:163]
	v_pk_add_f32 v[76:77], v[60:61], v[168:169]
	v_pk_add_f32 v[60:61], v[58:59], v[166:167]
	v_cvt_pk_bf16_f32 v58, v62, v63
	v_cvt_pk_bf16_f32 v59, v64, v65
	v_pk_add_f32 v[56:57], v[56:57], v[164:165]
	v_cvt_pk_bf16_f32 v60, v60, v61
	v_cvt_pk_bf16_f32 v61, v76, v77
	global_store_dwordx4 v[148:149], v[58:61], off offset:256
	v_pk_add_f32 v[54:55], v[54:55], v[162:163]
	v_pk_add_f32 v[48:49], v[48:49], v[164:165]
	v_pk_add_f32 v[58:59], v[52:53], v[168:169]
	v_pk_add_f32 v[52:53], v[50:51], v[166:167]
	v_cvt_pk_bf16_f32 v50, v54, v55
	v_cvt_pk_bf16_f32 v51, v56, v57
	v_pk_add_f32 v[46:47], v[46:47], v[162:163]
	v_cvt_pk_bf16_f32 v52, v52, v53
	v_cvt_pk_bf16_f32 v53, v58, v59
	global_store_dwordx4 v[114:115], v[50:53], off offset:256
	v_pk_add_f32 v[40:41], v[40:41], v[164:165]
	v_pk_add_f32 v[38:39], v[38:39], v[162:163]
	v_pk_add_f32 v[50:51], v[44:45], v[168:169]
	v_pk_add_f32 v[44:45], v[42:43], v[166:167]
	v_cvt_pk_bf16_f32 v42, v46, v47
	v_cvt_pk_bf16_f32 v43, v48, v49
	v_pk_add_f32 v[32:33], v[32:33], v[164:165]
	v_cvt_pk_bf16_f32 v44, v44, v45
	v_cvt_pk_bf16_f32 v45, v50, v51
	global_store_dwordx4 v[106:107], v[42:45], off offset:256
	v_pk_add_f32 v[30:31], v[30:31], v[162:163]
	v_pk_add_f32 v[24:25], v[24:25], v[164:165]
	v_pk_add_f32 v[42:43], v[36:37], v[168:169]
	v_pk_add_f32 v[36:37], v[34:35], v[166:167]
	v_cvt_pk_bf16_f32 v34, v38, v39
	v_cvt_pk_bf16_f32 v35, v40, v41
	v_pk_add_f32 v[22:23], v[22:23], v[162:163]
	v_cvt_pk_bf16_f32 v36, v36, v37
	v_cvt_pk_bf16_f32 v37, v42, v43
	global_store_dwordx4 v[98:99], v[34:37], off offset:256
	v_pk_add_f32 v[16:17], v[16:17], v[164:165]
	v_pk_add_f32 v[14:15], v[14:15], v[162:163]
	v_pk_add_f32 v[34:35], v[28:29], v[168:169]
	v_pk_add_f32 v[28:29], v[26:27], v[166:167]
	v_cvt_pk_bf16_f32 v26, v30, v31
	v_cvt_pk_bf16_f32 v27, v32, v33
	v_pk_add_f32 v[6:7], v[6:7], v[162:163]
	v_cvt_pk_bf16_f32 v28, v28, v29
	v_cvt_pk_bf16_f32 v29, v34, v35
	global_store_dwordx4 v[90:91], v[26:29], off offset:256
	v_pk_add_f32 v[8:9], v[8:9], v[164:165]
	s_nop 0
	v_pk_add_f32 v[26:27], v[20:21], v[168:169]
	v_pk_add_f32 v[20:21], v[18:19], v[166:167]
	v_cvt_pk_bf16_f32 v18, v22, v23
	v_cvt_pk_bf16_f32 v19, v24, v25
	s_nop 0
	v_cvt_pk_bf16_f32 v20, v20, v21
	v_cvt_pk_bf16_f32 v21, v26, v27
	global_store_dwordx4 v[82:83], v[18:21], off offset:256
	s_nop 1
	v_pk_add_f32 v[18:19], v[12:13], v[168:169]
	v_pk_add_f32 v[12:13], v[10:11], v[166:167]
	v_cvt_pk_bf16_f32 v10, v14, v15
	v_cvt_pk_bf16_f32 v11, v16, v17
	s_nop 0
	v_cvt_pk_bf16_f32 v12, v12, v13
	v_cvt_pk_bf16_f32 v13, v18, v19
	global_store_dwordx4 v[74:75], v[10:13], off offset:256
	s_nop 1
	v_pk_add_f32 v[10:11], v[4:5], v[168:169]
	v_pk_add_f32 v[4:5], v[2:3], v[166:167]
	v_cvt_pk_bf16_f32 v2, v6, v7
	v_add_co_u32_e32 v6, vcc, 0x58000, v148
	v_cvt_pk_bf16_f32 v3, v8, v9
	v_cvt_pk_bf16_f32 v4, v4, v5
	v_cvt_pk_bf16_f32 v5, v10, v11
	s_nop 1
	v_addc_co_u32_e32 v7, vcc, 0, v149, vcc
	global_store_dwordx4 v[6:7], v[2:5], off offset:256
	s_andn2_b64 vcc, exec, s[8:9]
	s_mov_b64 s[8:9], -1
	s_cbranch_vccnz .LBB0_186
	s_andn2_b64 vcc, exec, s[22:23]
	s_cbranch_vccnz .LBB0_185
	s_barrier
	s_branch .LBB0_185

.LBB0_1056:
	v_add_u32_e32 v158, s74, v149
	v_ashrrev_i32_e32 v159, 31, v158
	v_lshlrev_b64 v[158:159], 11, v[158:159]
	v_lshl_add_u64 v[158:159], s[62:63], 0, v[158:159]
	v_lshl_add_u64 v[158:159], v[158:159], 0, s[40:41]
	v_ashrrev_i32_e32 v149, 31, v148
	v_lshl_add_u64 v[148:149], v[148:149], 1, v[158:159]
	s_and_b64 vcc, exec, s[12:13]
	s_cbranch_vccnz .Lhb_null2
	v_lshl_add_u64 v[170:171], v[150:151], 2, s[60:61]
	global_load_dwordx4 v[162:165], v[170:171], off offset:512
	global_load_dwordx4 v[166:169], v[170:171], off offset:528
	s_branch .Lhb_done2

.Lhb_done2:
	s_waitcnt vmcnt(2)
	v_pk_add_f32 v[128:129], v[128:129], v[136:137]
	v_pk_add_f32 v[126:127], v[126:127], v[134:135]
	v_pk_add_f32 v[158:159], v[124:125], v[132:133]
	v_pk_add_f32 v[124:125], v[122:123], v[130:131]
	v_cvt_pk_bf16_f32 v122, v126, v127
	v_cvt_pk_bf16_f32 v123, v128, v129
	v_pk_add_f32 v[118:119], v[118:119], v[134:135]
	v_pk_add_f32 v[114:115], v[114:115], v[130:131]
	s_mov_b32 s0, 0x8000
	v_cvt_pk_bf16_f32 v124, v124, v125
	v_cvt_pk_bf16_f32 v125, v158, v159
	global_store_dwordx4 v[148:149], v[122:125], off
	v_pk_add_f32 v[120:121], v[120:121], v[136:137]
	v_pk_add_f32 v[110:111], v[110:111], v[134:135]
	v_pk_add_f32 v[122:123], v[116:117], v[132:133]
	v_cvt_pk_bf16_f32 v116, v118, v119
	v_cvt_pk_bf16_f32 v117, v120, v121
	v_cvt_pk_bf16_f32 v118, v114, v115
	v_add_co_u32_e32 v114, vcc, s0, v148
	v_pk_add_f32 v[106:107], v[106:107], v[130:131]
	s_nop 0
	v_addc_co_u32_e32 v115, vcc, 0, v149, vcc
	s_mov_b32 s0, 0x10000
	v_cvt_pk_bf16_f32 v119, v122, v123
	global_store_dwordx4 v[114:115], v[116:119], off
	v_pk_add_f32 v[112:113], v[112:113], v[136:137]
	v_pk_add_f32 v[102:103], v[102:103], v[134:135]
	v_pk_add_f32 v[116:117], v[108:109], v[132:133]
	v_cvt_pk_bf16_f32 v108, v110, v111
	v_cvt_pk_bf16_f32 v109, v112, v113
	v_cvt_pk_bf16_f32 v110, v106, v107
	v_add_co_u32_e32 v106, vcc, s0, v148
	v_pk_add_f32 v[98:99], v[98:99], v[130:131]
	s_nop 0
	v_addc_co_u32_e32 v107, vcc, 0, v149, vcc
	s_mov_b32 s0, 0x18000
	v_cvt_pk_bf16_f32 v111, v116, v117
	global_store_dwordx4 v[106:107], v[108:111], off
	v_pk_add_f32 v[104:105], v[104:105], v[136:137]
	v_pk_add_f32 v[94:95], v[94:95], v[134:135]
	v_pk_add_f32 v[108:109], v[100:101], v[132:133]
	v_cvt_pk_bf16_f32 v100, v102, v103
	v_cvt_pk_bf16_f32 v101, v104, v105
	v_cvt_pk_bf16_f32 v102, v98, v99
	v_add_co_u32_e32 v98, vcc, s0, v148
	v_pk_add_f32 v[90:91], v[90:91], v[130:131]
	s_nop 0
	v_addc_co_u32_e32 v99, vcc, 0, v149, vcc
	s_mov_b32 s0, 0x40000
	v_cvt_pk_bf16_f32 v103, v108, v109
	global_store_dwordx4 v[98:99], v[100:103], off
	v_pk_add_f32 v[96:97], v[96:97], v[136:137]
	v_pk_add_f32 v[86:87], v[86:87], v[134:135]
	v_pk_add_f32 v[100:101], v[92:93], v[132:133]
	v_cvt_pk_bf16_f32 v92, v94, v95
	v_cvt_pk_bf16_f32 v93, v96, v97
	v_cvt_pk_bf16_f32 v94, v90, v91
	v_add_co_u32_e32 v90, vcc, s0, v148
	v_pk_add_f32 v[82:83], v[82:83], v[130:131]
	s_nop 0
	v_addc_co_u32_e32 v91, vcc, 0, v149, vcc
	v_cvt_pk_bf16_f32 v95, v100, v101
	global_store_dwordx4 v[90:91], v[92:95], off
	v_pk_add_f32 v[88:89], v[88:89], v[136:137]
	v_pk_add_f32 v[78:79], v[78:79], v[134:135]
	v_pk_add_f32 v[92:93], v[84:85], v[132:133]
	v_cvt_pk_bf16_f32 v84, v86, v87
	v_cvt_pk_bf16_f32 v85, v88, v89
	v_cvt_pk_bf16_f32 v86, v82, v83
	v_add_co_u32_e32 v82, vcc, s80, v148
	v_pk_add_f32 v[74:75], v[74:75], v[130:131]
	s_nop 0
	v_addc_co_u32_e32 v83, vcc, 0, v149, vcc
	v_cvt_pk_bf16_f32 v87, v92, v93
	global_store_dwordx4 v[82:83], v[84:87], off
	v_pk_add_f32 v[80:81], v[80:81], v[136:137]
	v_pk_add_f32 v[70:71], v[70:71], v[134:135]
	v_pk_add_f32 v[84:85], v[76:77], v[132:133]
	v_cvt_pk_bf16_f32 v76, v78, v79
	v_cvt_pk_bf16_f32 v77, v80, v81
	v_cvt_pk_bf16_f32 v78, v74, v75
	v_add_co_u32_e32 v74, vcc, s81, v148
	v_cvt_pk_bf16_f32 v79, v84, v85
	v_pk_add_f32 v[72:73], v[72:73], v[136:137]
	s_nop 0
	v_addc_co_u32_e32 v75, vcc, 0, v149, vcc
	global_store_dwordx4 v[74:75], v[76:79], off
	s_nop 1
	v_pk_add_f32 v[76:77], v[68:69], v[132:133]
	v_pk_add_f32 v[68:69], v[66:67], v[130:131]
	v_cvt_pk_bf16_f32 v66, v70, v71
	v_add_co_u32_e32 v70, vcc, 0x58000, v148
	v_cvt_pk_bf16_f32 v67, v72, v73
	v_cvt_pk_bf16_f32 v68, v68, v69
	v_cvt_pk_bf16_f32 v69, v76, v77
	v_mov_b32_e32 v72, 0
	s_nop 0
	v_addc_co_u32_e32 v71, vcc, 0, v149, vcc
	global_store_dwordx4 v[70:71], v[66:69], off
	s_waitcnt vmcnt(8)
	v_pk_add_f32 v[64:65], v[64:65], v[164:165]
	v_pk_add_f32 v[62:63], v[62:63], v[162:163]
	v_pk_add_f32 v[76:77], v[60:61], v[168:169]
	v_pk_add_f32 v[60:61], v[58:59], v[166:167]
	v_cvt_pk_bf16_f32 v58, v62, v63
	v_cvt_pk_bf16_f32 v59, v64, v65
	v_pk_add_f32 v[56:57], v[56:57], v[164:165]
	v_cvt_pk_bf16_f32 v60, v60, v61
	v_cvt_pk_bf16_f32 v61, v76, v77
	global_store_dwordx4 v[148:149], v[58:61], off offset:256
	v_pk_add_f32 v[54:55], v[54:55], v[162:163]
	v_pk_add_f32 v[48:49], v[48:49], v[164:165]
	v_pk_add_f32 v[58:59], v[52:53], v[168:169]
	v_pk_add_f32 v[52:53], v[50:51], v[166:167]
	v_cvt_pk_bf16_f32 v50, v54, v55
	v_cvt_pk_bf16_f32 v51, v56, v57
	v_pk_add_f32 v[46:47], v[46:47], v[162:163]
	v_cvt_pk_bf16_f32 v52, v52, v53
	v_cvt_pk_bf16_f32 v53, v58, v59
	global_store_dwordx4 v[114:115], v[50:53], off offset:256
	v_pk_add_f32 v[40:41], v[40:41], v[164:165]
	v_pk_add_f32 v[38:39], v[38:39], v[162:163]
	v_pk_add_f32 v[50:51], v[44:45], v[168:169]
	v_pk_add_f32 v[44:45], v[42:43], v[166:167]
	v_cvt_pk_bf16_f32 v42, v46, v47
	v_cvt_pk_bf16_f32 v43, v48, v49
	v_pk_add_f32 v[32:33], v[32:33], v[164:165]
	v_cvt_pk_bf16_f32 v44, v44, v45
	v_cvt_pk_bf16_f32 v45, v50, v51
	global_store_dwordx4 v[106:107], v[42:45], off offset:256
	v_pk_add_f32 v[30:31], v[30:31], v[162:163]
	v_pk_add_f32 v[24:25], v[24:25], v[164:165]
	v_pk_add_f32 v[42:43], v[36:37], v[168:169]
	v_pk_add_f32 v[36:37], v[34:35], v[166:167]
	v_cvt_pk_bf16_f32 v34, v38, v39
	v_cvt_pk_bf16_f32 v35, v40, v41
	v_pk_add_f32 v[22:23], v[22:23], v[162:163]
	v_cvt_pk_bf16_f32 v36, v36, v37
	v_cvt_pk_bf16_f32 v37, v42, v43
	global_store_dwordx4 v[98:99], v[34:37], off offset:256
	v_pk_add_f32 v[16:17], v[16:17], v[164:165]
	v_pk_add_f32 v[14:15], v[14:15], v[162:163]
	v_pk_add_f32 v[34:35], v[28:29], v[168:169]
	v_pk_add_f32 v[28:29], v[26:27], v[166:167]
	v_cvt_pk_bf16_f32 v26, v30, v31
	v_cvt_pk_bf16_f32 v27, v32, v33
	v_pk_add_f32 v[6:7], v[6:7], v[162:163]
	v_cvt_pk_bf16_f32 v28, v28, v29
	v_cvt_pk_bf16_f32 v29, v34, v35
	global_store_dwordx4 v[90:91], v[26:29], off offset:256
	v_pk_add_f32 v[8:9], v[8:9], v[164:165]
	s_nop 0
	v_pk_add_f32 v[26:27], v[20:21], v[168:169]
	v_pk_add_f32 v[20:21], v[18:19], v[166:167]
	v_cvt_pk_bf16_f32 v18, v22, v23
	v_cvt_pk_bf16_f32 v19, v24, v25
	s_nop 0
	v_cvt_pk_bf16_f32 v20, v20, v21
	v_cvt_pk_bf16_f32 v21, v26, v27
	global_store_dwordx4 v[82:83], v[18:21], off offset:256
	s_nop 1
	v_pk_add_f32 v[18:19], v[12:13], v[168:169]
	v_pk_add_f32 v[12:13], v[10:11], v[166:167]
	v_cvt_pk_bf16_f32 v10, v14, v15
	v_cvt_pk_bf16_f32 v11, v16, v17
	s_nop 0
	v_cvt_pk_bf16_f32 v12, v12, v13
	v_cvt_pk_bf16_f32 v13, v18, v19
	global_store_dwordx4 v[74:75], v[10:13], off offset:256
	s_nop 1
	v_pk_add_f32 v[10:11], v[4:5], v[168:169]
	v_pk_add_f32 v[4:5], v[2:3], v[166:167]
	v_cvt_pk_bf16_f32 v2, v6, v7
	v_add_co_u32_e32 v6, vcc, 0x58000, v148
	v_cvt_pk_bf16_f32 v3, v8, v9
	v_cvt_pk_bf16_f32 v4, v4, v5
	v_cvt_pk_bf16_f32 v5, v10, v11
	s_nop 1
	v_addc_co_u32_e32 v7, vcc, 0, v149, vcc
	global_store_dwordx4 v[6:7], v[2:5], off offset:256
	s_andn2_b64 vcc, exec, s[10:11]
	s_mov_b64 s[10:11], -1
	s_cbranch_vccnz .LBB0_1045
	s_andn2_b64 vcc, exec, s[22:23]
	s_cbranch_vccnz .LBB0_1044
	s_barrier
	s_branch .LBB0_1044
